# v27 + MLP-in K-loop rewritten by hand as merged 64-MFMA segments: 2 barriers per K-tile instead of 4, second A half re-read in place, H0 waves issue 10 DMAs and H1 waves 6 per K-tile
# baseline (speedup 1.0000x reference)
.LBB0_1272:
	s_add_u32 s30, s28, 0xfff80080
	s_addc_u32 s31, s29, -1
	s_cmp_eq_u32 s65, 28
	s_cselect_b32 s37, s60, s31
	s_cselect_b32 s36, s61, s30
	s_cselect_b32 s31, s21, s64
	s_cselect_b32 s30, s62, s63
	s_add_u32 s100, s28, 0xfff80000
	s_addc_u32 s101, s29, -1
	s_add_u32 s68, s63, 0xffffff80
	s_addc_u32 s69, s64, -1
	v_add_u32_e32 v126, 0x10000, v156
	v_add_u32_e32 v170, 0x14000, v156
	ds_read_b128 v[114:117], v126
	ds_read_b128 v[118:121], v126 offset:1024
	ds_read_b128 v[122:125], v126 offset:2048
	ds_read_b128 v[126:129], v126 offset:3072
	ds_read_b128 v[158:161], v170
	ds_read_b128 v[162:165], v170 offset:1024
	ds_read_b128 v[166:169], v170 offset:2048
	ds_read_b128 v[170:173], v170 offset:3072
	ds_read_b128 v[174:177], v157
	ds_read_b128 v[178:181], v157 offset:1024
	ds_read_b128 v[182:185], v157 offset:2048
	ds_read_b128 v[186:189], v157 offset:3072
	ds_read_b128 v[190:193], v157 offset:4096
	ds_read_b128 v[202:205], v157 offset:5120
	ds_read_b128 v[206:209], v157 offset:6144
	ds_read_b128 v[210:213], v157 offset:7168
	s_and_b64 vcc, exec, s[18:19]
	s_cbranch_vccz .Lm64_h1_a
	s_add_u32 s66, s68, 0x0
	s_addc_u32 s67, s69, 0
	s_add_i32 m0, s48, 0x18000
	s_nop 0
	global_load_lds_dwordx4 v146, s[66:67]
	s_add_i32 m0, s48, 0x1a000
	s_nop 0
	global_load_lds_dwordx4 v148, s[66:67]
	s_add_u32 s66, s66, 0x20000
	s_addc_u32 s67, s67, 0
	s_add_i32 m0, s48, 0x19000
	s_nop 0
	global_load_lds_dwordx4 v146, s[66:67]
	s_add_i32 m0, s48, 0x1b000
	s_nop 0
	global_load_lds_dwordx4 v148, s[66:67]
	s_add_u32 s66, s68, 0x80000
	s_addc_u32 s67, s69, 0
	s_add_i32 m0, s48, 0x1c000
	s_nop 0
	global_load_lds_dwordx4 v146, s[66:67]
	s_add_i32 m0, s48, 0x1e000
	s_nop 0
	global_load_lds_dwordx4 v148, s[66:67]
	s_add_u32 s66, s66, 0x20000
	s_addc_u32 s67, s67, 0
	s_add_i32 m0, s48, 0x1d000
	s_nop 0
	global_load_lds_dwordx4 v146, s[66:67]
	s_add_i32 m0, s48, 0x1f000
	s_nop 0
	global_load_lds_dwordx4 v148, s[66:67]
	s_add_i32 m0, s48, 0x8000
	s_nop 0
	global_load_lds_dwordx4 v146, s[100:101]
	s_add_u32 s66, s100, 0x20000
	s_addc_u32 s67, s101, 0
	s_add_i32 m0, s48, 0x9000
	s_nop 0
	global_load_lds_dwordx4 v146, s[66:67]
	s_branch .Lm64_join_a
.Lm64_h1_a:
	s_add_i32 m0, s48, 0xa000
	s_nop 0
	global_load_lds_dwordx4 v148, s[100:101]
	s_add_u32 s66, s100, 0xfffe0000
	s_addc_u32 s67, s101, -1
	s_add_i32 m0, s48, 0x9000
	s_nop 0
	global_load_lds_dwordx4 v148, s[66:67]
	s_add_u32 s66, s100, 0x80000
	s_addc_u32 s67, s101, 0
	s_add_i32 m0, s48, 0xc000
	s_nop 0
	global_load_lds_dwordx4 v146, s[66:67]
	s_add_i32 m0, s48, 0xe000
	s_nop 0
	global_load_lds_dwordx4 v148, s[66:67]
	s_add_u32 s66, s66, 0xfffe0000
	s_addc_u32 s67, s67, -1
	s_add_i32 m0, s48, 0xb000
	s_nop 0
	global_load_lds_dwordx4 v146, s[66:67]
	s_add_i32 m0, s48, 0xd000
	s_nop 0
	global_load_lds_dwordx4 v148, s[66:67]
.Lm64_join_a:
	s_waitcnt lgkmcnt(0)
	s_setprio 1
	s_barrier
	v_mfma_f32_16x16x32_bf16 v[142:145], v[114:117], v[174:177], v[142:145]
	v_mfma_f32_16x16x32_bf16 v[142:145], v[118:121], v[178:181], v[142:145]
	v_mfma_f32_16x16x32_bf16 v[138:141], v[126:129], v[178:181], v[138:141]
	v_mfma_f32_16x16x32_bf16 v[138:141], v[122:125], v[174:177], v[138:141]
	v_mfma_f32_16x16x32_bf16 v[130:133], v[166:169], v[174:177], v[130:133]
	v_mfma_f32_16x16x32_bf16 v[130:133], v[170:173], v[178:181], v[130:133]
	v_mfma_f32_16x16x32_bf16 v[134:137], v[162:165], v[178:181], v[134:137]
	v_mfma_f32_16x16x32_bf16 v[134:137], v[158:161], v[174:177], v[134:137]
	ds_read_b128 v[174:177], v157 offset:16384
	ds_read_b128 v[178:181], v157 offset:17408
	v_mfma_f32_16x16x32_bf16 v[102:105], v[158:161], v[182:185], v[102:105]
	v_mfma_f32_16x16x32_bf16 v[102:105], v[162:165], v[186:189], v[102:105]
	v_mfma_f32_16x16x32_bf16 v[98:101], v[170:173], v[186:189], v[98:101]
	v_mfma_f32_16x16x32_bf16 v[98:101], v[166:169], v[182:185], v[98:101]
	v_mfma_f32_16x16x32_bf16 v[106:109], v[122:125], v[182:185], v[106:109]
	v_mfma_f32_16x16x32_bf16 v[106:109], v[126:129], v[186:189], v[106:109]
	v_mfma_f32_16x16x32_bf16 v[110:113], v[118:121], v[186:189], v[110:113]
	v_mfma_f32_16x16x32_bf16 v[110:113], v[114:117], v[182:185], v[110:113]
	ds_read_b128 v[182:185], v157 offset:18432
	ds_read_b128 v[186:189], v157 offset:19456
	v_mfma_f32_16x16x32_bf16 v[94:97], v[114:117], v[190:193], v[94:97]
	v_mfma_f32_16x16x32_bf16 v[94:97], v[118:121], v[202:205], v[94:97]
	v_mfma_f32_16x16x32_bf16 v[90:93], v[126:129], v[202:205], v[90:93]
	v_mfma_f32_16x16x32_bf16 v[90:93], v[122:125], v[190:193], v[90:93]
	v_mfma_f32_16x16x32_bf16 v[82:85], v[166:169], v[190:193], v[82:85]
	v_mfma_f32_16x16x32_bf16 v[82:85], v[170:173], v[202:205], v[82:85]
	v_mfma_f32_16x16x32_bf16 v[86:89], v[162:165], v[202:205], v[86:89]
	v_mfma_f32_16x16x32_bf16 v[86:89], v[158:161], v[190:193], v[86:89]
	ds_read_b128 v[190:193], v157 offset:20480
	ds_read_b128 v[202:205], v157 offset:21504
	v_mfma_f32_16x16x32_bf16 v[70:73], v[158:161], v[206:209], v[70:73]
	v_mfma_f32_16x16x32_bf16 v[70:73], v[162:165], v[210:213], v[70:73]
	v_mfma_f32_16x16x32_bf16 v[66:69], v[170:173], v[210:213], v[66:69]
	v_mfma_f32_16x16x32_bf16 v[66:69], v[166:169], v[206:209], v[66:69]
	v_mfma_f32_16x16x32_bf16 v[74:77], v[122:125], v[206:209], v[74:77]
	v_mfma_f32_16x16x32_bf16 v[74:77], v[126:129], v[210:213], v[74:77]
	v_mfma_f32_16x16x32_bf16 v[78:81], v[118:121], v[210:213], v[78:81]
	v_mfma_f32_16x16x32_bf16 v[78:81], v[114:117], v[206:209], v[78:81]
	ds_read_b128 v[206:209], v157 offset:22528
	ds_read_b128 v[210:213], v157 offset:23552
	s_waitcnt lgkmcnt(6)
	v_mfma_f32_16x16x32_bf16 v[62:65], v[114:117], v[174:177], v[62:65]
	v_mfma_f32_16x16x32_bf16 v[62:65], v[118:121], v[178:181], v[62:65]
	v_mfma_f32_16x16x32_bf16 v[58:61], v[126:129], v[178:181], v[58:61]
	v_mfma_f32_16x16x32_bf16 v[58:61], v[122:125], v[174:177], v[58:61]
	v_mfma_f32_16x16x32_bf16 v[50:53], v[166:169], v[174:177], v[50:53]
	v_mfma_f32_16x16x32_bf16 v[50:53], v[170:173], v[178:181], v[50:53]
	v_mfma_f32_16x16x32_bf16 v[54:57], v[162:165], v[178:181], v[54:57]
	v_mfma_f32_16x16x32_bf16 v[54:57], v[158:161], v[174:177], v[54:57]
	s_waitcnt lgkmcnt(4)
	v_mfma_f32_16x16x32_bf16 v[38:41], v[158:161], v[182:185], v[38:41]
	v_mfma_f32_16x16x32_bf16 v[38:41], v[162:165], v[186:189], v[38:41]
	v_mfma_f32_16x16x32_bf16 v[34:37], v[170:173], v[186:189], v[34:37]
	v_mfma_f32_16x16x32_bf16 v[34:37], v[166:169], v[182:185], v[34:37]
	v_mfma_f32_16x16x32_bf16 v[42:45], v[122:125], v[182:185], v[42:45]
	v_mfma_f32_16x16x32_bf16 v[42:45], v[126:129], v[186:189], v[42:45]
	v_mfma_f32_16x16x32_bf16 v[46:49], v[118:121], v[186:189], v[46:49]
	v_mfma_f32_16x16x32_bf16 v[46:49], v[114:117], v[182:185], v[46:49]
	s_waitcnt lgkmcnt(2)
	v_mfma_f32_16x16x32_bf16 v[30:33], v[114:117], v[190:193], v[30:33]
	v_mfma_f32_16x16x32_bf16 v[30:33], v[118:121], v[202:205], v[30:33]
	v_mfma_f32_16x16x32_bf16 v[26:29], v[126:129], v[202:205], v[26:29]
	v_mfma_f32_16x16x32_bf16 v[26:29], v[122:125], v[190:193], v[26:29]
	v_mfma_f32_16x16x32_bf16 v[18:21], v[166:169], v[190:193], v[18:21]
	v_mfma_f32_16x16x32_bf16 v[18:21], v[170:173], v[202:205], v[18:21]
	v_mfma_f32_16x16x32_bf16 v[22:25], v[162:165], v[202:205], v[22:25]
	v_mfma_f32_16x16x32_bf16 v[22:25], v[158:161], v[190:193], v[22:25]
	s_waitcnt lgkmcnt(0)
	v_mfma_f32_16x16x32_bf16 v[6:9], v[158:161], v[206:209], v[6:9]
	v_mfma_f32_16x16x32_bf16 v[6:9], v[162:165], v[210:213], v[6:9]
	v_mfma_f32_16x16x32_bf16 v[2:5], v[170:173], v[210:213], v[2:5]
	v_mfma_f32_16x16x32_bf16 v[2:5], v[166:169], v[206:209], v[2:5]
	v_mfma_f32_16x16x32_bf16 v[10:13], v[122:125], v[206:209], v[10:13]
	v_mfma_f32_16x16x32_bf16 v[10:13], v[126:129], v[210:213], v[10:13]
	v_mfma_f32_16x16x32_bf16 v[14:17], v[118:121], v[210:213], v[14:17]
	v_mfma_f32_16x16x32_bf16 v[14:17], v[114:117], v[206:209], v[14:17]
	s_waitcnt vmcnt(0)
	s_barrier
	s_setprio 0
	v_add_u32_e32 v126, 0x18000, v156
	v_add_u32_e32 v170, 0x1c000, v156
	ds_read_b128 v[114:117], v126
	ds_read_b128 v[118:121], v126 offset:1024
	ds_read_b128 v[122:125], v126 offset:2048
	ds_read_b128 v[126:129], v126 offset:3072
	ds_read_b128 v[158:161], v170
	ds_read_b128 v[162:165], v170 offset:1024
	ds_read_b128 v[166:169], v170 offset:2048
	ds_read_b128 v[170:173], v170 offset:3072
	ds_read_b128 v[174:177], v157 offset:32768
	ds_read_b128 v[178:181], v157 offset:33792
	ds_read_b128 v[182:185], v157 offset:34816
	ds_read_b128 v[186:189], v157 offset:35840
	ds_read_b128 v[190:193], v157 offset:36864
	ds_read_b128 v[202:205], v157 offset:37888
	ds_read_b128 v[206:209], v157 offset:38912
	ds_read_b128 v[210:213], v157 offset:39936
	s_and_b64 vcc, exec, s[18:19]
	s_cbranch_vccz .Lm64_h1_b
	s_add_u32 s66, s30, 0x0
	s_addc_u32 s67, s31, 0
	s_add_i32 m0, s48, 0x10000
	s_nop 0
	global_load_lds_dwordx4 v146, s[66:67]
	s_add_i32 m0, s48, 0x12000
	s_nop 0
	global_load_lds_dwordx4 v148, s[66:67]
	s_add_u32 s66, s66, 0x20000
	s_addc_u32 s67, s67, 0
	s_add_i32 m0, s48, 0x11000
	s_nop 0
	global_load_lds_dwordx4 v146, s[66:67]
	s_add_i32 m0, s48, 0x13000
	s_nop 0
	global_load_lds_dwordx4 v148, s[66:67]
	s_add_u32 s66, s30, 0x80000
	s_addc_u32 s67, s31, 0
	s_add_i32 m0, s48, 0x14000
	s_nop 0
	global_load_lds_dwordx4 v146, s[66:67]
	s_add_i32 m0, s48, 0x16000
	s_nop 0
	global_load_lds_dwordx4 v148, s[66:67]
	s_add_u32 s66, s66, 0x20000
	s_addc_u32 s67, s67, 0
	s_add_i32 m0, s48, 0x15000
	s_nop 0
	global_load_lds_dwordx4 v146, s[66:67]
	s_add_i32 m0, s48, 0x17000
	s_nop 0
	global_load_lds_dwordx4 v148, s[66:67]
	s_add_i32 m0, s48, 0x0
	s_nop 0
	global_load_lds_dwordx4 v146, s[36:37]
	s_add_u32 s66, s36, 0x20000
	s_addc_u32 s67, s37, 0
	s_add_i32 m0, s48, 0x1000
	s_nop 0
	global_load_lds_dwordx4 v146, s[66:67]
	s_branch .Lm64_join_b
.Lm64_h1_b:
	s_add_i32 m0, s48, 0x2000
	s_nop 0
	global_load_lds_dwordx4 v148, s[36:37]
	s_add_u32 s66, s36, 0xfffe0000
	s_addc_u32 s67, s37, -1
	s_add_i32 m0, s48, 0x1000
	s_nop 0
	global_load_lds_dwordx4 v148, s[66:67]
	s_add_u32 s66, s36, 0x80000
	s_addc_u32 s67, s37, 0
	s_add_i32 m0, s48, 0x4000
	s_nop 0
	global_load_lds_dwordx4 v146, s[66:67]
	s_add_i32 m0, s48, 0x6000
	s_nop 0
	global_load_lds_dwordx4 v148, s[66:67]
	s_add_u32 s66, s66, 0xfffe0000
	s_addc_u32 s67, s67, -1
	s_add_i32 m0, s48, 0x3000
	s_nop 0
	global_load_lds_dwordx4 v146, s[66:67]
	s_add_i32 m0, s48, 0x5000
	s_nop 0
	global_load_lds_dwordx4 v148, s[66:67]
.Lm64_join_b:
	s_waitcnt lgkmcnt(0)
	s_setprio 1
	s_barrier
	v_mfma_f32_16x16x32_bf16 v[142:145], v[114:117], v[174:177], v[142:145]
	v_mfma_f32_16x16x32_bf16 v[142:145], v[118:121], v[178:181], v[142:145]
	v_mfma_f32_16x16x32_bf16 v[138:141], v[126:129], v[178:181], v[138:141]
	v_mfma_f32_16x16x32_bf16 v[138:141], v[122:125], v[174:177], v[138:141]
	v_mfma_f32_16x16x32_bf16 v[130:133], v[166:169], v[174:177], v[130:133]
	v_mfma_f32_16x16x32_bf16 v[130:133], v[170:173], v[178:181], v[130:133]
	v_mfma_f32_16x16x32_bf16 v[134:137], v[162:165], v[178:181], v[134:137]
	v_mfma_f32_16x16x32_bf16 v[134:137], v[158:161], v[174:177], v[134:137]
	ds_read_b128 v[174:177], v157 offset:49152
	ds_read_b128 v[178:181], v157 offset:50176
	v_mfma_f32_16x16x32_bf16 v[102:105], v[158:161], v[182:185], v[102:105]
	v_mfma_f32_16x16x32_bf16 v[102:105], v[162:165], v[186:189], v[102:105]
	v_mfma_f32_16x16x32_bf16 v[98:101], v[170:173], v[186:189], v[98:101]
	v_mfma_f32_16x16x32_bf16 v[98:101], v[166:169], v[182:185], v[98:101]
	v_mfma_f32_16x16x32_bf16 v[106:109], v[122:125], v[182:185], v[106:109]
	v_mfma_f32_16x16x32_bf16 v[106:109], v[126:129], v[186:189], v[106:109]
	v_mfma_f32_16x16x32_bf16 v[110:113], v[118:121], v[186:189], v[110:113]
	v_mfma_f32_16x16x32_bf16 v[110:113], v[114:117], v[182:185], v[110:113]
	ds_read_b128 v[182:185], v157 offset:51200
	ds_read_b128 v[186:189], v157 offset:52224
	v_mfma_f32_16x16x32_bf16 v[94:97], v[114:117], v[190:193], v[94:97]
	v_mfma_f32_16x16x32_bf16 v[94:97], v[118:121], v[202:205], v[94:97]
	v_mfma_f32_16x16x32_bf16 v[90:93], v[126:129], v[202:205], v[90:93]
	v_mfma_f32_16x16x32_bf16 v[90:93], v[122:125], v[190:193], v[90:93]
	v_mfma_f32_16x16x32_bf16 v[82:85], v[166:169], v[190:193], v[82:85]
	v_mfma_f32_16x16x32_bf16 v[82:85], v[170:173], v[202:205], v[82:85]
	v_mfma_f32_16x16x32_bf16 v[86:89], v[162:165], v[202:205], v[86:89]
	v_mfma_f32_16x16x32_bf16 v[86:89], v[158:161], v[190:193], v[86:89]
	ds_read_b128 v[190:193], v157 offset:53248
	ds_read_b128 v[202:205], v157 offset:54272
	v_mfma_f32_16x16x32_bf16 v[70:73], v[158:161], v[206:209], v[70:73]
	v_mfma_f32_16x16x32_bf16 v[70:73], v[162:165], v[210:213], v[70:73]
	v_mfma_f32_16x16x32_bf16 v[66:69], v[170:173], v[210:213], v[66:69]
	v_mfma_f32_16x16x32_bf16 v[66:69], v[166:169], v[206:209], v[66:69]
	v_mfma_f32_16x16x32_bf16 v[74:77], v[122:125], v[206:209], v[74:77]
	v_mfma_f32_16x16x32_bf16 v[74:77], v[126:129], v[210:213], v[74:77]
	v_mfma_f32_16x16x32_bf16 v[78:81], v[118:121], v[210:213], v[78:81]
	v_mfma_f32_16x16x32_bf16 v[78:81], v[114:117], v[206:209], v[78:81]
	ds_read_b128 v[206:209], v157 offset:55296
	ds_read_b128 v[210:213], v157 offset:56320
	s_waitcnt lgkmcnt(6)
	v_mfma_f32_16x16x32_bf16 v[62:65], v[114:117], v[174:177], v[62:65]
	v_mfma_f32_16x16x32_bf16 v[62:65], v[118:121], v[178:181], v[62:65]
	v_mfma_f32_16x16x32_bf16 v[58:61], v[126:129], v[178:181], v[58:61]
	v_mfma_f32_16x16x32_bf16 v[58:61], v[122:125], v[174:177], v[58:61]
	v_mfma_f32_16x16x32_bf16 v[50:53], v[166:169], v[174:177], v[50:53]
	v_mfma_f32_16x16x32_bf16 v[50:53], v[170:173], v[178:181], v[50:53]
	v_mfma_f32_16x16x32_bf16 v[54:57], v[162:165], v[178:181], v[54:57]
	v_mfma_f32_16x16x32_bf16 v[54:57], v[158:161], v[174:177], v[54:57]
	s_waitcnt lgkmcnt(4)
	v_mfma_f32_16x16x32_bf16 v[38:41], v[158:161], v[182:185], v[38:41]
	v_mfma_f32_16x16x32_bf16 v[38:41], v[162:165], v[186:189], v[38:41]
	v_mfma_f32_16x16x32_bf16 v[34:37], v[170:173], v[186:189], v[34:37]
	v_mfma_f32_16x16x32_bf16 v[34:37], v[166:169], v[182:185], v[34:37]
	v_mfma_f32_16x16x32_bf16 v[42:45], v[122:125], v[182:185], v[42:45]
	v_mfma_f32_16x16x32_bf16 v[42:45], v[126:129], v[186:189], v[42:45]
	v_mfma_f32_16x16x32_bf16 v[46:49], v[118:121], v[186:189], v[46:49]
	v_mfma_f32_16x16x32_bf16 v[46:49], v[114:117], v[182:185], v[46:49]
	s_waitcnt lgkmcnt(2)
	v_mfma_f32_16x16x32_bf16 v[30:33], v[114:117], v[190:193], v[30:33]
	v_mfma_f32_16x16x32_bf16 v[30:33], v[118:121], v[202:205], v[30:33]
	v_mfma_f32_16x16x32_bf16 v[26:29], v[126:129], v[202:205], v[26:29]
	v_mfma_f32_16x16x32_bf16 v[26:29], v[122:125], v[190:193], v[26:29]
	v_mfma_f32_16x16x32_bf16 v[18:21], v[166:169], v[190:193], v[18:21]
	v_mfma_f32_16x16x32_bf16 v[18:21], v[170:173], v[202:205], v[18:21]
	v_mfma_f32_16x16x32_bf16 v[22:25], v[162:165], v[202:205], v[22:25]
	v_mfma_f32_16x16x32_bf16 v[22:25], v[158:161], v[190:193], v[22:25]
	s_waitcnt lgkmcnt(0)
	v_mfma_f32_16x16x32_bf16 v[6:9], v[158:161], v[206:209], v[6:9]
	v_mfma_f32_16x16x32_bf16 v[6:9], v[162:165], v[210:213], v[6:9]
	v_mfma_f32_16x16x32_bf16 v[2:5], v[170:173], v[210:213], v[2:5]
	v_mfma_f32_16x16x32_bf16 v[2:5], v[166:169], v[206:209], v[2:5]
	v_mfma_f32_16x16x32_bf16 v[10:13], v[122:125], v[206:209], v[10:13]
	v_mfma_f32_16x16x32_bf16 v[10:13], v[126:129], v[210:213], v[10:13]
	v_mfma_f32_16x16x32_bf16 v[14:17], v[118:121], v[210:213], v[14:17]
	v_mfma_f32_16x16x32_bf16 v[14:17], v[114:117], v[206:209], v[14:17]
	s_waitcnt vmcnt(0)
	s_barrier
	s_setprio 0
	s_add_i32 s65, s65, 2
	s_add_u32 s28, s28, 0x100
	s_addc_u32 s29, s29, 0
	s_add_u32 s63, s63, 0x100
	s_addc_u32 s64, s64, 0
	s_cmp_gt_u32 s65, 29
	s_cbranch_scc0 .LBB0_1272
	s_and_b64 vcc, exec, s[18:19]
	s_cbranch_vccz .LBB0_1275
	s_barrier

	.amdhsa_kernel _Z4mega8MegaArgs
		.amdhsa_group_segment_fixed_size 0
		.amdhsa_private_segment_fixed_size 0
		.amdhsa_kernarg_size 496
		.amdhsa_user_sgpr_count 2
		.amdhsa_user_sgpr_dispatch_ptr 0
		.amdhsa_user_sgpr_queue_ptr 0
		.amdhsa_user_sgpr_kernarg_segment_ptr 1
		.amdhsa_user_sgpr_dispatch_id 0
		.amdhsa_user_sgpr_kernarg_preload_length 0
		.amdhsa_user_sgpr_kernarg_preload_offset 0
		.amdhsa_user_sgpr_private_segment_size 0
		.amdhsa_uses_dynamic_stack 0
		.amdhsa_enable_private_segment 0
		.amdhsa_system_sgpr_workgroup_id_x 1
		.amdhsa_system_sgpr_workgroup_id_y 0
		.amdhsa_system_sgpr_workgroup_id_z 0
		.amdhsa_system_sgpr_workgroup_info 0
		.amdhsa_system_vgpr_workitem_id 0
		.amdhsa_next_free_vgpr 256
		.amdhsa_next_free_sgpr 102
		.amdhsa_accum_offset 256
		.amdhsa_reserve_vcc 1
		.amdhsa_float_round_mode_32 0
		.amdhsa_float_round_mode_16_64 0
		.amdhsa_float_denorm_mode_32 3
		.amdhsa_float_denorm_mode_16_64 3
		.amdhsa_dx10_clamp 1
		.amdhsa_ieee_mode 1
		.amdhsa_fp16_overflow 0
		.amdhsa_tg_split 0
		.amdhsa_exception_fp_ieee_invalid_op 0
		.amdhsa_exception_fp_denorm_src 0
		.amdhsa_exception_fp_ieee_div_zero 0
		.amdhsa_exception_fp_ieee_overflow 0
		.amdhsa_exception_fp_ieee_underflow 0
		.amdhsa_exception_fp_ieee_inexact 0
		.amdhsa_exception_int_div_zero 0
	.end_amdhsa_kernel

amdhsa.kernels:
  - .agpr_count:     0
    .args:
      - .offset:         0
        .size:           240
        .value_kind:     by_value
      - .offset:         240
        .size:           4
        .value_kind:     hidden_block_count_x
      - .offset:         244
        .size:           4
        .value_kind:     hidden_block_count_y
      - .offset:         248
        .size:           4
        .value_kind:     hidden_block_count_z
      - .offset:         252
        .size:           2
        .value_kind:     hidden_group_size_x
      - .offset:         254
        .size:           2
        .value_kind:     hidden_group_size_y
      - .offset:         256
        .size:           2
        .value_kind:     hidden_group_size_z
      - .offset:         258
        .size:           2
        .value_kind:     hidden_remainder_x
      - .offset:         260
        .size:           2
        .value_kind:     hidden_remainder_y
      - .offset:         262
        .size:           2
        .value_kind:     hidden_remainder_z
      - .offset:         280
        .size:           8
        .value_kind:     hidden_global_offset_x
      - .offset:         288
        .size:           8
        .value_kind:     hidden_global_offset_y
      - .offset:         296
        .size:           8
        .value_kind:     hidden_global_offset_z
      - .offset:         304
        .size:           2
        .value_kind:     hidden_grid_dims
      - .offset:         360
        .size:           4
        .value_kind:     hidden_dynamic_lds_size
    .group_segment_fixed_size: 0
    .kernarg_segment_align: 8
    .kernarg_segment_size: 496
    .language:       OpenCL C
    .language_version:
      - 2
      - 0
    .max_flat_workgroup_size: 512
    .name:           _Z4mega8MegaArgs
    .private_segment_fixed_size: 0
    .sgpr_count:     108
    .sgpr_spill_count: 282
    .symbol:         _Z4mega8MegaArgs.kd
    .uniform_work_group_size: 1
    .uses_dynamic_stack: false
    .vgpr_count:     256
    .vgpr_spill_count: 0
    .wavefront_size: 64
